# layer-0 out phase: half of each XCD's WGs (blockIdx bit 3) run the layer-1 weight re-conversion before their out-projection tile (power/bandwidth mixing)
# baseline (speedup 1.0000x reference)
.LBB0_759:
	s_or_b64 exec, exec, s[0:1]
	s_mov_b32 s32, 0
	s_bitcmp1_b32 s52, 3
	s_cbranch_scc0 .Lout_P
	s_mov_b32 s32, 1
	s_mov_b64 s[26:27], s[4:5]
	s_mov_b32 s2, s96
	s_mov_b32 s3, s97
	s_branch .LBB0_771
.Lout_P:
	s_mov_b64 s[0:1], 0
	s_waitcnt lgkmcnt(0)
	s_barrier
	s_add_u32 s2, s96, s0
	v_mov_b32_e32 v14, v197
	s_addc_u32 s3, s97, s1
	s_barrier
	s_and_b64 vcc, exec, s[4:5]
	v_readfirstlane_b32 s14, v14
	s_cbranch_vccnz .LBB0_771
	v_lshlrev_b32_e32 v0, 4, v14
	v_add_u32_e32 v1, 0x2000, v0
	v_ashrrev_i32_e32 v2, 31, v1
	v_lshrrev_b32_e32 v2, 22, v2
	v_add_u32_e32 v2, v1, v2
	v_ashrrev_i32_e32 v8, 10, v2
	v_mul_i32_i24_e32 v3, 0x400, v8
	v_sub_u32_e32 v1, v1, v3
	v_lshrrev_b32_e32 v3, 4, v1
	v_bitop3_b32 v1, v3, v1, 32 bitop3:0x6c
	v_ashrrev_i32_e32 v3, 31, v1
	v_lshrrev_b32_e32 v3, 26, v3
	v_add_u32_e32 v3, v1, v3
	v_ashrrev_i32_e32 v9, 6, v3
	v_and_b32_e32 v3, 0xc0, v3
	v_sub_u32_e32 v1, v1, v3
	v_lshlrev_b32_e32 v2, 5, v8
	v_ashrrev_i16_sdwa v1, v221, sext(v1) dst_sel:DWORD dst_unused:UNUSED_PAD src0_sel:DWORD src1_sel:BYTE_0
	v_and_b32_e32 v2, 32, v2
	v_bfe_i32 v10, v1, 0, 16
	v_add_u32_e32 v1, v2, v10
	v_lshlrev_b32_e32 v2, 3, v8
	v_and_b32_e32 v2, 0x1ffff0, v2
	v_add_lshl_u32 v2, v9, v2, 11
	v_lshl_add_u32 v136, v1, 1, v2
	v_bfe_i32 v2, v14, 27, 1
	v_lshrrev_b32_e32 v2, 22, v2
	v_add_u32_e32 v2, v0, v2
	v_and_b32_e32 v2, 0xfffffc00, v2
	v_sub_u32_e32 v0, v0, v2
	v_lshrrev_b32_e32 v2, 4, v0
	s_add_u32 s15, s2, 0xb000000
	s_mov_b32 s51, s91
	v_bitop3_b32 v2, v2, v0, 32 bitop3:0x6c
	v_ashrrev_i32_e32 v0, 31, v0
	s_addc_u32 s16, s3, 0
	s_lshl_b64 s[0:1], s[50:51], 21
	v_lshrrev_b32_e32 v0, 26, v0
	s_add_u32 s0, s2, s0
	v_ashrrev_i32_e32 v1, 31, v14
	v_add_u32_e32 v0, v2, v0
	s_addc_u32 s1, s3, s1
	v_lshrrev_b32_e32 v1, 26, v1
	v_ashrrev_i32_e32 v12, 6, v0
	s_add_u32 s17, s0, 0x10500000
	v_add_u32_e32 v1, v14, v1
	v_mul_i32_i24_e32 v0, 64, v12
	s_addc_u32 s18, s1, 0
	s_ashr_i32 s0, s14, 6
	v_ashrrev_i32_e32 v11, 6, v1
	v_sub_u32_e32 v0, v2, v0
	s_ashr_i32 s1, s14, 8
	s_lshl_b32 s19, s0, 10
	v_lshlrev_b32_e32 v1, 5, v11
	v_ashrrev_i16_sdwa v0, v221, sext(v0) dst_sel:DWORD dst_unused:UNUSED_PAD src0_sel:DWORD src1_sel:BYTE_0
	v_and_b32_e32 v1, 32, v1
	v_bfe_i32 v13, v0, 0, 16
	s_add_u32 s8, s15, s65
	v_add_u32_e32 v0, v1, v13
	v_lshlrev_b32_e32 v1, 3, v11
	s_addc_u32 s9, s16, 0
	v_and_b32_e32 v1, 0x1ffff0, v1
	s_add_u32 s10, s17, s66
	v_add_lshl_u32 v1, v12, v1, 11
	s_addc_u32 s11, s18, 0
	s_add_i32 s20, s19, 0
	v_lshl_add_u32 v194, v0, 1, v1
	s_add_i32 m0, s20, 0x10000
	s_add_i32 s21, s20, 0x2000
	global_load_lds_dwordx4 v194, s[10:11]
	s_add_i32 m0, s20, 0x12000
	s_add_u32 s4, s10, 0x40000
	global_load_lds_dwordx4 v136, s[10:11]
	s_mov_b32 m0, s20
	s_addc_u32 s5, s11, 0
	global_load_lds_dwordx4 v194, s[8:9]
	s_mov_b32 m0, s21
	v_mov_b32_e32 v137, v195
	global_load_lds_dwordx4 v136, s[8:9]
	s_add_i32 m0, s20, 0x14000
	v_lshl_add_u64 v[6:7], s[10:11], 0, v[194:195]
	global_load_lds_dwordx4 v194, s[4:5]
	s_add_i32 m0, s20, 0x16000
	v_lshl_add_u64 v[4:5], s[10:11], 0, v[136:137]
	global_load_lds_dwordx4 v136, s[4:5]
	s_add_u32 s4, s8, 0x40000
	s_addc_u32 s5, s9, 0
	s_add_i32 s22, s20, 0x4000
	s_mov_b32 m0, s22
	s_add_i32 s23, s20, 0x6000
	global_load_lds_dwordx4 v194, s[4:5]
	s_mov_b32 m0, s23
	v_lshl_add_u64 v[2:3], s[8:9], 0, v[194:195]
	global_load_lds_dwordx4 v136, s[4:5]
	s_cmp_lg_u32 s1, 1
	v_lshl_add_u64 v[0:1], s[8:9], 0, v[136:137]
	s_cbranch_scc1 .LBB0_762
	s_barrier

.LBB0_771:
	v_readlane_b32 s0, v252, 23
	v_readlane_b32 s1, v252, 24
	s_andn2_b64 vcc, exec, s[0:1]
	s_waitcnt lgkmcnt(0)
	s_barrier
	s_cmp_eq_u32 s32, 2
	s_cbranch_scc1 .LBB0_808
	s_cbranch_vccnz .LBB0_808
	v_readlane_b32 s0, v253, 48
	v_readlane_b32 s1, v253, 49
	v_mov_b32_e32 v8, v197
	s_andn2_b64 vcc, exec, s[0:1]
	s_cbranch_vccnz .LBB0_808
	v_readlane_b32 s0, v253, 59
	v_ashrrev_i32_e32 v12, 4, v8
	v_lshlrev_b32_e32 v0, 2, v8
	v_readlane_b32 s4, v253, 52
	v_readlane_b32 s1, v253, 60
	v_and_b32_e32 v10, 60, v0
	v_add_u32_e32 v2, s4, v12
	v_mov_b64_e32 v[0:1], s[0:1]
	s_mov_b32 s5, 0x8800
	v_mad_i64_i32 v[2:3], s[0:1], v2, s5, v[0:1]
	v_readlane_b32 s0, v253, 53
	v_lshlrev_b32_e32 v194, 2, v10
	v_lshl_add_u64 v[2:3], v[2:3], 0, v[194:195]
	v_add_u32_e32 v4, s0, v12
	v_mad_i64_i32 v[0:1], s[0:1], v4, s5, v[0:1]
	v_lshl_add_u64 v[4:5], v[0:1], 0, v[194:195]
	global_load_dwordx4 v[0:3], v[2:3], off
	s_nop 0
	global_load_dwordx4 v[4:7], v[4:5], off
	s_add_u32 s0, s2, 0xf000000
	s_movk_i32 s2, 0x104
	v_ashrrev_i32_e32 v14, 3, v8
	v_lshlrev_b32_e32 v8, 3, v8
	v_mul_lo_u32 v9, v12, s2
	v_and_b32_e32 v16, 56, v8
	v_readlane_b32 s6, v253, 55
	s_addc_u32 s1, s3, 0
	v_add3_u32 v13, 0, v9, v194
	v_mad_u32_u24 v15, v16, s2, 0
	v_lshlrev_b32_e32 v8, 2, v10
	v_lshlrev_b32_e32 v194, 1, v16
	v_readlane_b32 s2, v252, 0
	v_readlane_b32 s3, v253, 63
	v_readlane_b32 s10, v253, 50
	s_mov_b32 s5, s6
	s_mov_b32 s23, s52
	v_readlane_b32 s7, v253, 56
	s_branch .LBB0_775

.LBB0_808:
	s_cmp_eq_u32 s32, 1
	s_cbranch_scc0 .Lout_end
	s_mov_b32 s32, 2
	s_mov_b64 s[4:5], s[26:27]
	s_branch .Lout_P
